# P8 prompt attention QK loop: next Q fragment requested at the top of the step into its own registers
# speedup vs baseline: 1.0091x; 1.0091x over previous
.LBB0_1408:
	s_cmpk_lg_i32 s57, 0x100
	s_cselect_b32 s20, s57, 0xf0
	v_lshl_add_u64 v[200:201], s[20:21], 1, v[158:159]
	global_load_dwordx4 v[238:241], v[200:201], off
	v_xor_b32_e32 v155, v134, v164
	v_lshl_add_u32 v155, v155, 4, v165
	ds_read_b128 v[192:195], v155
	ds_read_b128 v[196:199], v155 offset:16384
	v_add_u32_e32 v157, 0x10000, v155
	v_add_u32_e32 v191, 0x14000, v155
	s_waitcnt vmcnt(1) lgkmcnt(1)
	v_mfma_f32_32x32x16_bf16 v[114:129], v[192:195], v[130:133], v[114:129]
	s_add_i32 s57, s57, 16
	v_add_u32_e32 v134, 2, v134
	s_cmpk_eq_i32 s57, 0x110
	s_waitcnt lgkmcnt(0)
	v_mfma_f32_32x32x16_bf16 v[98:113], v[196:199], v[130:133], v[98:113]
	ds_read_b128 v[192:195], v155 offset:32768
	ds_read_b128 v[196:199], v155 offset:49152
	s_waitcnt lgkmcnt(1)
	v_mfma_f32_32x32x16_bf16 v[82:97], v[192:195], v[130:133], v[82:97]
	s_waitcnt lgkmcnt(0)
	v_mfma_f32_32x32x16_bf16 v[66:81], v[196:199], v[130:133], v[66:81]
	ds_read_b128 v[192:195], v157
	ds_read_b128 v[196:199], v191
	v_add_u32_e32 v157, 0x18000, v155
	v_add_u32_e32 v155, 0x1c000, v155
	s_waitcnt lgkmcnt(1)
	v_mfma_f32_32x32x16_bf16 v[50:65], v[192:195], v[130:133], v[50:65]
	s_waitcnt lgkmcnt(0)
	v_mfma_f32_32x32x16_bf16 v[34:49], v[196:199], v[130:133], v[34:49]
	ds_read_b128 v[192:195], v157
	ds_read_b128 v[196:199], v155
	s_waitcnt lgkmcnt(1)
	v_mfma_f32_32x32x16_bf16 v[18:33], v[192:195], v[130:133], v[18:33]
	s_waitcnt lgkmcnt(0)
	v_mfma_f32_32x32x16_bf16 v[2:17], v[196:199], v[130:133], v[2:17]
	s_waitcnt vmcnt(0)
	v_mov_b64_e32 v[130:131], v[238:239]
	v_mov_b64_e32 v[132:133], v[240:241]
	s_cbranch_scc0 .LBB0_1408
	v_max3_f32 v130, v114, s61, v115
	v_max3_f32 v130, v130, v116, v117
	v_max3_f32 v130, v130, v118, v119
	v_max3_f32 v130, v130, v120, v121
	v_max3_f32 v130, v130, v122, v123
	v_max3_f32 v130, v130, v124, v125
	v_max3_f32 v130, v130, v126, v127
	v_max3_f32 v130, v130, v128, v129
	v_max3_f32 v130, v130, v98, v99
	v_max3_f32 v130, v130, v100, v101
	v_max3_f32 v130, v130, v102, v103
	v_max3_f32 v130, v130, v104, v105
	v_max3_f32 v130, v130, v106, v107
	v_max3_f32 v130, v130, v108, v109
	v_max3_f32 v130, v130, v110, v111
	v_max3_f32 v130, v130, v112, v113
	v_max3_f32 v130, v130, v82, v83
	v_max3_f32 v130, v130, v84, v85
	v_max3_f32 v130, v130, v86, v87
	v_max3_f32 v130, v130, v88, v89
	v_max3_f32 v130, v130, v90, v91
	v_max3_f32 v130, v130, v92, v93
	v_max3_f32 v130, v130, v94, v95
	v_max3_f32 v130, v130, v96, v97
	v_max3_f32 v130, v130, v66, v67
	v_max3_f32 v130, v130, v68, v69
	v_max3_f32 v130, v130, v70, v71
	v_max3_f32 v130, v130, v72, v73
	v_max3_f32 v130, v130, v74, v75
	v_max3_f32 v130, v130, v76, v77
	v_max3_f32 v130, v130, v78, v79
	v_max3_f32 v130, v130, v80, v81
	v_max3_f32 v130, v130, v50, v51
	v_max3_f32 v130, v130, v52, v53
	v_max3_f32 v130, v130, v54, v55
	v_max3_f32 v130, v130, v56, v57
	v_max3_f32 v130, v130, v58, v59
	v_max3_f32 v130, v130, v60, v61
	v_max3_f32 v130, v130, v62, v63
	v_max3_f32 v130, v130, v64, v65
	v_max3_f32 v130, v130, v34, v35
	v_max3_f32 v130, v130, v36, v37
	v_max3_f32 v130, v130, v38, v39
	v_max3_f32 v130, v130, v40, v41
	v_max3_f32 v130, v130, v42, v43
	v_max3_f32 v130, v130, v44, v45
	v_max3_f32 v130, v130, v46, v47
	v_max3_f32 v130, v130, v48, v49
	v_max3_f32 v130, v130, v18, v19
	v_max3_f32 v130, v130, v20, v21
	v_max3_f32 v130, v130, v22, v23
	v_max3_f32 v130, v130, v24, v25
	v_max3_f32 v130, v130, v26, v27
	v_max3_f32 v130, v130, v28, v29
	v_max3_f32 v130, v130, v30, v31
	v_max3_f32 v130, v130, v32, v33
	v_max3_f32 v130, v130, v2, v3
	v_max3_f32 v130, v130, v4, v5
	v_max3_f32 v130, v130, v6, v7
	v_max3_f32 v130, v130, v8, v9
	v_max3_f32 v130, v130, v10, v11
	v_max3_f32 v130, v130, v12, v13
	v_max3_f32 v130, v130, v14, v15
	v_max3_f32 v130, v130, v16, v17
	ds_bpermute_b32 v131, v153, v130
	s_lshl_b32 s20, s56, 2
	s_or_b32 s56, s20, s63
	s_ashr_i32 s57, s56, 31
	s_lshl_b64 s[56:57], s[56:57], 17
	s_waitcnt lgkmcnt(0)
	v_max_f32_e32 v131, v131, v131
	v_max_f32_e32 v134, v130, v131
	v_sub_f32_e32 v114, v114, v134
	v_sub_f32_e32 v115, v115, v134
	v_exp_f32_e32 v114, v114
	v_sub_f32_e32 v116, v116, v134
	v_exp_f32_e32 v115, v115
	v_sub_f32_e32 v117, v117, v134
	v_exp_f32_e32 v116, v116
	v_sub_f32_e32 v118, v118, v134
	v_exp_f32_e32 v117, v117
	v_add_f32_e32 v130, 0, v114
	v_exp_f32_e32 v118, v118
	v_sub_f32_e32 v119, v119, v134
	v_add_f32_e32 v130, v115, v130
	v_exp_f32_e32 v119, v119
	v_sub_f32_e32 v120, v120, v134
	v_add_f32_e32 v130, v116, v130
	v_exp_f32_e32 v120, v120
	v_sub_f32_e32 v121, v121, v134
	v_add_f32_e32 v130, v117, v130
	v_exp_f32_e32 v121, v121
	v_sub_f32_e32 v122, v122, v134
	v_add_f32_e32 v130, v118, v130
	v_exp_f32_e32 v122, v122
	v_sub_f32_e32 v123, v123, v134
	v_add_f32_e32 v130, v119, v130
	v_exp_f32_e32 v123, v123
	v_sub_f32_e32 v124, v124, v134
	v_add_f32_e32 v130, v120, v130
	v_exp_f32_e32 v124, v124
	v_sub_f32_e32 v125, v125, v134
	v_add_f32_e32 v130, v121, v130
	v_exp_f32_e32 v125, v125
	v_sub_f32_e32 v126, v126, v134
	v_add_f32_e32 v130, v122, v130
	v_exp_f32_e32 v126, v126
	v_sub_f32_e32 v127, v127, v134
	v_add_f32_e32 v130, v123, v130
	v_exp_f32_e32 v127, v127
	v_sub_f32_e32 v128, v128, v134
	v_add_f32_e32 v130, v124, v130
	v_exp_f32_e32 v128, v128
	v_sub_f32_e32 v129, v129, v134
	v_add_f32_e32 v130, v125, v130
	v_exp_f32_e32 v129, v129
	v_sub_f32_e32 v98, v98, v134
	v_add_f32_e32 v130, v126, v130
	v_exp_f32_e32 v98, v98
	v_sub_f32_e32 v99, v99, v134
	v_add_f32_e32 v130, v127, v130
	v_exp_f32_e32 v99, v99
	v_sub_f32_e32 v100, v100, v134
	v_add_f32_e32 v130, v128, v130
	v_exp_f32_e32 v100, v100
	v_sub_f32_e32 v101, v101, v134
	v_add_f32_e32 v130, v129, v130
	v_exp_f32_e32 v101, v101
	v_sub_f32_e32 v102, v102, v134
	v_add_f32_e32 v130, v98, v130
	v_exp_f32_e32 v102, v102
	v_sub_f32_e32 v103, v103, v134
	v_add_f32_e32 v130, v99, v130
	v_exp_f32_e32 v103, v103
	v_sub_f32_e32 v104, v104, v134
	v_add_f32_e32 v130, v100, v130
	v_exp_f32_e32 v104, v104
	v_sub_f32_e32 v105, v105, v134
	v_add_f32_e32 v130, v101, v130
	v_exp_f32_e32 v105, v105
	v_sub_f32_e32 v106, v106, v134
	v_add_f32_e32 v130, v102, v130
	v_exp_f32_e32 v106, v106
	v_sub_f32_e32 v107, v107, v134
	v_add_f32_e32 v130, v103, v130
	v_exp_f32_e32 v107, v107
	v_sub_f32_e32 v108, v108, v134
	v_add_f32_e32 v130, v104, v130
	v_exp_f32_e32 v108, v108
	v_sub_f32_e32 v109, v109, v134
	v_add_f32_e32 v130, v105, v130
	v_exp_f32_e32 v109, v109
	v_sub_f32_e32 v110, v110, v134
	v_add_f32_e32 v130, v106, v130
	v_exp_f32_e32 v110, v110
	v_sub_f32_e32 v111, v111, v134
	v_add_f32_e32 v130, v107, v130
	v_exp_f32_e32 v111, v111
	v_sub_f32_e32 v112, v112, v134
	v_add_f32_e32 v130, v108, v130
	v_exp_f32_e32 v112, v112
	v_sub_f32_e32 v113, v113, v134
	v_add_f32_e32 v130, v109, v130
	v_exp_f32_e32 v113, v113
	v_sub_f32_e32 v82, v82, v134
	v_add_f32_e32 v130, v110, v130
	v_exp_f32_e32 v82, v82
	v_sub_f32_e32 v83, v83, v134
	v_add_f32_e32 v130, v111, v130
	v_exp_f32_e32 v83, v83
	v_sub_f32_e32 v84, v84, v134
	v_add_f32_e32 v130, v112, v130
	v_exp_f32_e32 v84, v84
	v_sub_f32_e32 v85, v85, v134
	v_add_f32_e32 v130, v113, v130
	v_exp_f32_e32 v85, v85
	v_sub_f32_e32 v86, v86, v134
	v_add_f32_e32 v130, v82, v130
	v_exp_f32_e32 v86, v86
	v_sub_f32_e32 v87, v87, v134
	v_add_f32_e32 v130, v83, v130
	v_exp_f32_e32 v87, v87
	v_sub_f32_e32 v88, v88, v134
	v_add_f32_e32 v130, v84, v130
	v_exp_f32_e32 v88, v88
	v_sub_f32_e32 v89, v89, v134
	v_add_f32_e32 v130, v85, v130
	v_exp_f32_e32 v89, v89
	v_sub_f32_e32 v90, v90, v134
	v_add_f32_e32 v130, v86, v130
	v_exp_f32_e32 v90, v90
	v_sub_f32_e32 v91, v91, v134
	v_add_f32_e32 v130, v87, v130
	v_exp_f32_e32 v91, v91
	v_sub_f32_e32 v92, v92, v134
	v_add_f32_e32 v130, v88, v130
	v_exp_f32_e32 v92, v92
	v_sub_f32_e32 v93, v93, v134
	v_add_f32_e32 v130, v89, v130
	v_exp_f32_e32 v93, v93
	v_sub_f32_e32 v94, v94, v134
	v_add_f32_e32 v130, v90, v130
	v_exp_f32_e32 v94, v94
	v_sub_f32_e32 v95, v95, v134
	v_add_f32_e32 v130, v91, v130
	v_exp_f32_e32 v95, v95
	v_sub_f32_e32 v96, v96, v134
	v_add_f32_e32 v130, v92, v130
	v_exp_f32_e32 v96, v96
	v_sub_f32_e32 v97, v97, v134
	v_add_f32_e32 v130, v93, v130
	v_exp_f32_e32 v97, v97
	v_sub_f32_e32 v66, v66, v134
	v_add_f32_e32 v130, v94, v130
	v_exp_f32_e32 v66, v66
	v_sub_f32_e32 v67, v67, v134
	v_add_f32_e32 v130, v95, v130
	v_exp_f32_e32 v67, v67
	v_sub_f32_e32 v68, v68, v134
	v_add_f32_e32 v130, v96, v130
	v_exp_f32_e32 v68, v68
	v_sub_f32_e32 v69, v69, v134
	v_add_f32_e32 v130, v97, v130
	v_exp_f32_e32 v69, v69
	v_sub_f32_e32 v70, v70, v134
	v_add_f32_e32 v130, v66, v130
	v_exp_f32_e32 v70, v70
	v_sub_f32_e32 v71, v71, v134
	v_add_f32_e32 v130, v67, v130
	v_exp_f32_e32 v71, v71
	v_sub_f32_e32 v72, v72, v134
	v_add_f32_e32 v130, v68, v130
	v_exp_f32_e32 v72, v72
	v_sub_f32_e32 v73, v73, v134
	v_add_f32_e32 v130, v69, v130
	v_exp_f32_e32 v73, v73
	v_sub_f32_e32 v74, v74, v134
	v_add_f32_e32 v130, v70, v130
	v_exp_f32_e32 v74, v74
	v_sub_f32_e32 v75, v75, v134
	v_add_f32_e32 v130, v71, v130
	v_exp_f32_e32 v75, v75
	v_sub_f32_e32 v76, v76, v134
	v_add_f32_e32 v130, v72, v130
	v_exp_f32_e32 v76, v76
	v_sub_f32_e32 v77, v77, v134
	v_add_f32_e32 v130, v73, v130
	v_exp_f32_e32 v77, v77
	v_sub_f32_e32 v78, v78, v134
	v_add_f32_e32 v130, v74, v130
	v_exp_f32_e32 v78, v78
	v_sub_f32_e32 v79, v79, v134
	v_add_f32_e32 v130, v75, v130
	v_exp_f32_e32 v79, v79
	v_sub_f32_e32 v80, v80, v134
	v_add_f32_e32 v130, v76, v130
	v_exp_f32_e32 v80, v80
	v_sub_f32_e32 v81, v81, v134
	v_add_f32_e32 v130, v77, v130
	v_exp_f32_e32 v81, v81
	v_sub_f32_e32 v50, v50, v134
	v_add_f32_e32 v130, v78, v130
	v_exp_f32_e32 v50, v50
	v_sub_f32_e32 v51, v51, v134
	v_add_f32_e32 v130, v79, v130
	v_exp_f32_e32 v51, v51
	v_sub_f32_e32 v52, v52, v134
	v_add_f32_e32 v130, v80, v130
	v_exp_f32_e32 v52, v52
	v_sub_f32_e32 v53, v53, v134
	v_add_f32_e32 v130, v81, v130
	v_exp_f32_e32 v53, v53
	v_sub_f32_e32 v54, v54, v134
	v_add_f32_e32 v130, v50, v130
	v_exp_f32_e32 v54, v54
	v_sub_f32_e32 v55, v55, v134
	v_add_f32_e32 v130, v51, v130
	v_exp_f32_e32 v55, v55
	v_sub_f32_e32 v56, v56, v134
	v_add_f32_e32 v130, v52, v130
	v_exp_f32_e32 v56, v56
	v_sub_f32_e32 v57, v57, v134
	v_add_f32_e32 v130, v53, v130
	v_exp_f32_e32 v57, v57
	v_sub_f32_e32 v58, v58, v134
	v_add_f32_e32 v130, v54, v130
	v_exp_f32_e32 v58, v58
	v_sub_f32_e32 v59, v59, v134
	v_add_f32_e32 v130, v55, v130
	v_exp_f32_e32 v59, v59
	v_sub_f32_e32 v60, v60, v134
	v_add_f32_e32 v130, v56, v130
	v_exp_f32_e32 v60, v60
	v_sub_f32_e32 v61, v61, v134
	v_add_f32_e32 v130, v57, v130
	v_exp_f32_e32 v61, v61
	v_sub_f32_e32 v62, v62, v134
	v_add_f32_e32 v130, v58, v130
	v_exp_f32_e32 v62, v62
	v_sub_f32_e32 v63, v63, v134
	v_add_f32_e32 v130, v59, v130
	v_exp_f32_e32 v63, v63
	v_sub_f32_e32 v64, v64, v134
	v_add_f32_e32 v130, v60, v130
	v_exp_f32_e32 v64, v64
	v_sub_f32_e32 v65, v65, v134
	v_add_f32_e32 v130, v61, v130
	v_exp_f32_e32 v65, v65
	v_add_f32_e32 v130, v62, v130
	v_add_f32_e32 v130, v63, v130
	v_add_f32_e32 v130, v64, v130
	v_sub_f32_e32 v34, v34, v134
	v_add_f32_e32 v155, v65, v130
	v_exp_f32_e32 v130, v34
	v_sub_f32_e32 v34, v35, v134
	v_exp_f32_e32 v131, v34
	v_sub_f32_e32 v34, v36, v134
	v_exp_f32_e32 v132, v34
	v_sub_f32_e32 v34, v37, v134
	v_exp_f32_e32 v133, v34
	v_sub_f32_e32 v35, v38, v134
	v_add_f32_e32 v34, v130, v155
	v_exp_f32_e32 v155, v35
	v_sub_f32_e32 v35, v39, v134
	v_add_f32_e32 v34, v131, v34
	v_exp_f32_e32 v157, v35
	v_sub_f32_e32 v35, v40, v134
	v_add_f32_e32 v34, v132, v34
	v_exp_f32_e32 v158, v35
	v_sub_f32_e32 v35, v41, v134
	v_add_f32_e32 v34, v133, v34
	v_exp_f32_e32 v159, v35
	v_sub_f32_e32 v35, v42, v134
	v_add_f32_e32 v34, v155, v34
	v_exp_f32_e32 v191, v35
	v_sub_f32_e32 v35, v43, v134
	v_add_f32_e32 v34, v157, v34
	v_exp_f32_e32 v192, v35
	v_sub_f32_e32 v35, v44, v134
	v_add_f32_e32 v34, v158, v34
	v_exp_f32_e32 v193, v35
	v_sub_f32_e32 v35, v45, v134
	v_add_f32_e32 v34, v159, v34
	v_exp_f32_e32 v194, v35
	v_sub_f32_e32 v35, v46, v134
	v_add_f32_e32 v34, v191, v34
	v_exp_f32_e32 v195, v35
	v_sub_f32_e32 v35, v47, v134
	v_add_f32_e32 v34, v192, v34
	v_exp_f32_e32 v196, v35
	v_sub_f32_e32 v35, v48, v134
	v_add_f32_e32 v34, v193, v34
	v_exp_f32_e32 v197, v35
	v_sub_f32_e32 v35, v49, v134
	v_add_f32_e32 v34, v194, v34
	v_exp_f32_e32 v198, v35
	v_sub_f32_e32 v18, v18, v134
	v_add_f32_e32 v34, v195, v34
	v_exp_f32_e32 v199, v18
	v_sub_f32_e32 v18, v19, v134
	v_add_f32_e32 v34, v196, v34
	v_exp_f32_e32 v200, v18
	v_sub_f32_e32 v18, v20, v134
	v_add_f32_e32 v34, v197, v34
	v_exp_f32_e32 v201, v18
	v_sub_f32_e32 v18, v21, v134
	v_add_f32_e32 v34, v198, v34
	v_exp_f32_e32 v202, v18
	v_sub_f32_e32 v19, v22, v134
	v_add_f32_e32 v18, v199, v34
	v_exp_f32_e32 v203, v19
	v_sub_f32_e32 v19, v23, v134
	v_add_f32_e32 v18, v200, v18
	v_exp_f32_e32 v204, v19
	v_sub_f32_e32 v19, v24, v134
	v_add_f32_e32 v18, v201, v18
	v_exp_f32_e32 v205, v19
	v_sub_f32_e32 v19, v25, v134
	v_add_f32_e32 v18, v202, v18
	v_exp_f32_e32 v206, v19
	v_sub_f32_e32 v19, v26, v134
	v_add_f32_e32 v18, v203, v18
	v_exp_f32_e32 v207, v19
	v_sub_f32_e32 v19, v27, v134
	v_add_f32_e32 v18, v204, v18
	v_exp_f32_e32 v208, v19
	v_sub_f32_e32 v19, v28, v134
	v_add_f32_e32 v18, v205, v18
	v_exp_f32_e32 v209, v19
	v_sub_f32_e32 v19, v29, v134
	v_add_f32_e32 v18, v206, v18
	v_exp_f32_e32 v210, v19
	v_sub_f32_e32 v19, v30, v134
	v_add_f32_e32 v18, v207, v18
	v_exp_f32_e32 v211, v19
	v_sub_f32_e32 v19, v31, v134
	v_add_f32_e32 v18, v208, v18
	v_exp_f32_e32 v212, v19
	v_sub_f32_e32 v19, v32, v134
	v_add_f32_e32 v18, v209, v18
	v_exp_f32_e32 v213, v19
	v_sub_f32_e32 v19, v33, v134
	v_add_f32_e32 v18, v210, v18
	v_exp_f32_e32 v214, v19
	v_sub_f32_e32 v2, v2, v134
	v_add_f32_e32 v18, v211, v18
	v_exp_f32_e32 v215, v2
	v_sub_f32_e32 v2, v3, v134
	v_add_f32_e32 v18, v212, v18
	v_exp_f32_e32 v216, v2
	v_sub_f32_e32 v2, v4, v134
	v_add_f32_e32 v18, v213, v18
	v_exp_f32_e32 v4, v2
	v_sub_f32_e32 v2, v5, v134
	v_add_f32_e32 v18, v214, v18
	v_exp_f32_e32 v5, v2
	v_sub_f32_e32 v3, v6, v134
	v_add_f32_e32 v2, v215, v18
	v_exp_f32_e32 v6, v3
	v_sub_f32_e32 v3, v7, v134
	v_add_f32_e32 v2, v216, v2
	v_exp_f32_e32 v7, v3
	v_sub_f32_e32 v3, v8, v134
	v_add_f32_e32 v2, v4, v2
	v_exp_f32_e32 v8, v3
	v_sub_f32_e32 v3, v9, v134
	v_add_f32_e32 v2, v5, v2
	v_exp_f32_e32 v9, v3
	v_sub_f32_e32 v3, v10, v134
	v_add_f32_e32 v2, v6, v2
	v_exp_f32_e32 v10, v3
	v_sub_f32_e32 v3, v11, v134
	v_add_f32_e32 v2, v7, v2
	v_exp_f32_e32 v11, v3
	v_sub_f32_e32 v3, v12, v134
	v_add_f32_e32 v2, v8, v2
	v_exp_f32_e32 v12, v3
	v_sub_f32_e32 v3, v13, v134
	v_add_f32_e32 v2, v9, v2
	v_exp_f32_e32 v13, v3
	v_sub_f32_e32 v3, v14, v134
	v_add_f32_e32 v2, v10, v2
	v_exp_f32_e32 v14, v3
	v_sub_f32_e32 v3, v15, v134
	v_add_f32_e32 v2, v11, v2
	v_exp_f32_e32 v15, v3
	v_sub_f32_e32 v3, v16, v134
	v_add_f32_e32 v2, v12, v2
	v_exp_f32_e32 v217, v3
	v_sub_f32_e32 v3, v17, v134
	v_add_f32_e32 v2, v13, v2
	v_exp_f32_e32 v218, v3
	v_add_f32_e32 v2, v14, v2
	v_add_f32_e32 v2, v15, v2
	v_add_f32_e32 v2, v217, v2
	v_add_f32_e32 v16, v218, v2
	ds_bpermute_b32 v17, v153, v16
	v_lshl_add_u64 v[2:3], v[146:147], 0, s[56:57]
	s_mov_b32 s20, 0
	s_mov_b64 s[56:57], -1
	s_waitcnt lgkmcnt(0)
	s_barrier
